# u-loop flag simplification plus second accumulator shift-init moved behind the first QK MFMA
# baseline (speedup 1.0000x reference)
.LBB0_883:
	v_mad_u32_u24 v203, v203, s82, v201
	ds_read_b128 v[204:207], v203
	ds_read_b128 v[208:211], v203 offset:32
	s_nop 5
	v_xor_b32_e32 v80, 0x80000000, v199
	v_mov_b32_e32 v81, v80
	v_mov_b32_e32 v82, v80
	v_mov_b32_e32 v83, v80
	v_mov_b32_e32 v84, v80
	v_mov_b32_e32 v85, v80
	v_mov_b32_e32 v86, v80
	v_mov_b32_e32 v87, v80
	v_mov_b32_e32 v88, v80
	v_mov_b32_e32 v89, v80
	v_mov_b32_e32 v90, v80
	v_mov_b32_e32 v91, v80
	v_mov_b32_e32 v92, v80
	v_mov_b32_e32 v93, v80
	v_mov_b32_e32 v94, v80
	v_mov_b32_e32 v95, v80
	s_waitcnt lgkmcnt(0)
	v_mfma_f32_32x32x16_bf16 v[80:95], v[204:207], v[96:99], v[80:95]
	v_xor_b32_e32 v64, 0x80000000, v200
	v_mov_b32_e32 v65, v64
	v_mov_b32_e32 v66, v64
	v_mov_b32_e32 v67, v64
	v_mov_b32_e32 v68, v64
	v_mov_b32_e32 v69, v64
	v_mov_b32_e32 v70, v64
	v_mov_b32_e32 v71, v64
	v_mov_b32_e32 v72, v64
	v_mov_b32_e32 v73, v64
	v_mov_b32_e32 v74, v64
	v_mov_b32_e32 v75, v64
	v_mov_b32_e32 v76, v64
	v_mov_b32_e32 v77, v64
	v_mov_b32_e32 v78, v64
	v_mov_b32_e32 v79, v64
	v_mfma_f32_32x32x16_bf16 v[64:79], v[204:207], v[136:139], v[64:79]
	v_mfma_f32_32x32x16_bf16 v[80:95], v[208:211], v[100:103], v[80:95]
	v_mfma_f32_32x32x16_bf16 v[64:79], v[208:211], v[120:123], v[64:79]
	ds_read_b128 v[204:207], v203 offset:64
	ds_read_b128 v[208:211], v203 offset:96
	s_waitcnt lgkmcnt(0)
	v_mfma_f32_32x32x16_bf16 v[80:95], v[204:207], v[104:107], v[80:95]
	v_mfma_f32_32x32x16_bf16 v[64:79], v[204:207], v[124:127], v[64:79]
	v_mfma_f32_32x32x16_bf16 v[80:95], v[208:211], v[108:111], v[80:95]
	v_mfma_f32_32x32x16_bf16 v[64:79], v[208:211], v[128:131], v[64:79]
	ds_read_b128 v[204:207], v203 offset:128
	ds_read_b128 v[208:211], v203 offset:160
	s_waitcnt lgkmcnt(0)
	v_mfma_f32_32x32x16_bf16 v[80:95], v[204:207], v[112:115], v[80:95]
	v_mfma_f32_32x32x16_bf16 v[64:79], v[204:207], v[132:135], v[64:79]
	v_mfma_f32_32x32x16_bf16 v[80:95], v[208:211], v[116:119], v[80:95]
	v_mfma_f32_32x32x16_bf16 v[64:79], v[208:211], v[140:143], v[64:79]
	s_branch .LBB0_885

.LBB0_2117:
	v_mad_u32_u24 v203, v203, s81, v201
	ds_read_b128 v[204:207], v203
	ds_read_b128 v[208:211], v203 offset:32
	s_nop 5
	v_xor_b32_e32 v80, 0x80000000, v199
	v_mov_b32_e32 v81, v80
	v_mov_b32_e32 v82, v80
	v_mov_b32_e32 v83, v80
	v_mov_b32_e32 v84, v80
	v_mov_b32_e32 v85, v80
	v_mov_b32_e32 v86, v80
	v_mov_b32_e32 v87, v80
	v_mov_b32_e32 v88, v80
	v_mov_b32_e32 v89, v80
	v_mov_b32_e32 v90, v80
	v_mov_b32_e32 v91, v80
	v_mov_b32_e32 v92, v80
	v_mov_b32_e32 v93, v80
	v_mov_b32_e32 v94, v80
	v_mov_b32_e32 v95, v80
	s_waitcnt lgkmcnt(0)
	v_mfma_f32_32x32x16_bf16 v[80:95], v[204:207], v[96:99], v[80:95]
	v_xor_b32_e32 v64, 0x80000000, v200
	v_mov_b32_e32 v65, v64
	v_mov_b32_e32 v66, v64
	v_mov_b32_e32 v67, v64
	v_mov_b32_e32 v68, v64
	v_mov_b32_e32 v69, v64
	v_mov_b32_e32 v70, v64
	v_mov_b32_e32 v71, v64
	v_mov_b32_e32 v72, v64
	v_mov_b32_e32 v73, v64
	v_mov_b32_e32 v74, v64
	v_mov_b32_e32 v75, v64
	v_mov_b32_e32 v76, v64
	v_mov_b32_e32 v77, v64
	v_mov_b32_e32 v78, v64
	v_mov_b32_e32 v79, v64
	v_mfma_f32_32x32x16_bf16 v[64:79], v[204:207], v[136:139], v[64:79]
	v_mfma_f32_32x32x16_bf16 v[80:95], v[208:211], v[100:103], v[80:95]
	v_mfma_f32_32x32x16_bf16 v[64:79], v[208:211], v[120:123], v[64:79]
	ds_read_b128 v[204:207], v203 offset:64
	ds_read_b128 v[208:211], v203 offset:96
	s_waitcnt lgkmcnt(0)
	v_mfma_f32_32x32x16_bf16 v[80:95], v[204:207], v[104:107], v[80:95]
	v_mfma_f32_32x32x16_bf16 v[64:79], v[204:207], v[124:127], v[64:79]
	v_mfma_f32_32x32x16_bf16 v[80:95], v[208:211], v[108:111], v[80:95]
	v_mfma_f32_32x32x16_bf16 v[64:79], v[208:211], v[128:131], v[64:79]
	ds_read_b128 v[204:207], v203 offset:128
	ds_read_b128 v[208:211], v203 offset:160
	s_waitcnt lgkmcnt(0)
	v_mfma_f32_32x32x16_bf16 v[80:95], v[204:207], v[112:115], v[80:95]
	v_mfma_f32_32x32x16_bf16 v[64:79], v[204:207], v[132:135], v[64:79]
	v_mfma_f32_32x32x16_bf16 v[80:95], v[208:211], v[116:119], v[80:95]
	v_mfma_f32_32x32x16_bf16 v[64:79], v[208:211], v[140:143], v[64:79]
	s_branch .LBB0_2119
